# GEMM phases: per-cluster s_setprio toggles removed; one static s_setprio 1 for waves 0-3 per GEMM phase
# speedup vs baseline: 1.0044x; 1.0044x over previous
.Lsp_gemm:
	v_readfirstlane_b32 s100, v206
	s_nop 3
	s_cmp_ge_u32 s100, 0x100
	s_cbranch_scc1 .Lsp_done
	s_setprio 1
